# code placement: attention-phase code shifted by 4 bytes (A/B/C tile loop heads to 0 mod 8), downstream GEMM placement unchanged
# speedup vs baseline: 1.0102x; 1.0018x over previous
; #define ATT_WAIT_BAR() asm volatile("s_waitcnt vmcnt(0) lgkmcnt(0)\n\ts_barrier" ::: "memory")
; DI void attn_phase(const Params& P, char* shm) {
;     ...
;     for (unsigned k = 0; k < 8; ++k) {
;         const unsigned q = (xcd + k) & 7u; unsigned* cnt = P.counter + 16 * q;
;         for (;;) {
;             if (tid == 0) su[0] = atomicAdd(cnt, 1u);
;             ATT_WAIT_BAR();
;             const unsigned ui = su[0];
;             ATT_WAIT_BAR();
;             if (ui >= 384u) break;
;             const unsigned e = P.order[q * 384 + ui]; const int kind = e >> 28, b = (e >> 24) & 15, h = (e >> 16) & 255, qb = e & 0xffff;
.LBB0_316:
	s_nop 0
	v_writelane_b32 v255, 0, 61
	s_nop 0
	s_mov_b32 s0, 0x40000000
	v_writelane_b32 v255, s0, 62
	s_nop 0
	v_readlane_b32 s0, v255, 29
	s_add_i32 s0, s1, s0
	v_writelane_b32 v255, s1, 45
	s_and_b32 s0, s0, 7
	s_lshl_b32 s1, s0, 6
	v_readlane_b32 s2, v255, 25
	s_add_u32 s42, s2, s1
	v_readlane_b32 s1, v255, 26
	s_mul_i32 s41, s0, 0x180
	s_addc_u32 s43, s1, 0
	v_writelane_b32 v255, s41, 46
	v_writelane_b32 v255, s42, 47
	s_nop 1
	v_writelane_b32 v255, s43, 48
	s_branch .LBB0_320

; DI void attn_phase(const Params& P, char* shm) {
;     ...
;     __builtin_amdgcn_s_setprio(0);
.LBB0_438:
	s_nop 0
	s_setprio 0
	s_mov_b64 s[0:1], 0
